# attention hot QK MFMA block issued at raised wave priority (s_setprio 1 .. 0), on top of u-loop flag simplification
# speedup vs baseline: 1.0089x; 1.0089x over previous
.LBB0_883:
	v_mad_u32_u24 v203, v203, s82, v201
	ds_read_b128 v[204:207], v203
	ds_read_b128 v[208:211], v203 offset:32
	s_nop 5
	v_xor_b32_e32 v80, 0x80000000, v199
	v_xor_b32_e32 v64, 0x80000000, v200
	v_mov_b32_e32 v81, v80
	v_mov_b32_e32 v82, v80
	v_mov_b32_e32 v83, v80
	v_mov_b32_e32 v84, v80
	v_mov_b32_e32 v85, v80
	v_mov_b32_e32 v86, v80
	v_mov_b32_e32 v87, v80
	v_mov_b32_e32 v88, v80
	v_mov_b32_e32 v89, v80
	v_mov_b32_e32 v90, v80
	v_mov_b32_e32 v91, v80
	v_mov_b32_e32 v92, v80
	v_mov_b32_e32 v93, v80
	v_mov_b32_e32 v94, v80
	v_mov_b32_e32 v95, v80
	v_mov_b32_e32 v65, v64
	v_mov_b32_e32 v66, v64
	v_mov_b32_e32 v67, v64
	v_mov_b32_e32 v68, v64
	v_mov_b32_e32 v69, v64
	v_mov_b32_e32 v70, v64
	v_mov_b32_e32 v71, v64
	v_mov_b32_e32 v72, v64
	v_mov_b32_e32 v73, v64
	v_mov_b32_e32 v74, v64
	v_mov_b32_e32 v75, v64
	v_mov_b32_e32 v76, v64
	v_mov_b32_e32 v77, v64
	v_mov_b32_e32 v78, v64
	v_mov_b32_e32 v79, v64
	s_waitcnt lgkmcnt(0)
	s_setprio 1
	v_mfma_f32_32x32x16_bf16 v[80:95], v[204:207], v[96:99], v[80:95]
	v_mfma_f32_32x32x16_bf16 v[64:79], v[204:207], v[136:139], v[64:79]
	v_mfma_f32_32x32x16_bf16 v[80:95], v[208:211], v[100:103], v[80:95]
	v_mfma_f32_32x32x16_bf16 v[64:79], v[208:211], v[120:123], v[64:79]
	ds_read_b128 v[204:207], v203 offset:64
	ds_read_b128 v[208:211], v203 offset:96
	s_waitcnt lgkmcnt(0)
	v_mfma_f32_32x32x16_bf16 v[80:95], v[204:207], v[104:107], v[80:95]
	v_mfma_f32_32x32x16_bf16 v[64:79], v[204:207], v[124:127], v[64:79]
	v_mfma_f32_32x32x16_bf16 v[80:95], v[208:211], v[108:111], v[80:95]
	v_mfma_f32_32x32x16_bf16 v[64:79], v[208:211], v[128:131], v[64:79]
	ds_read_b128 v[204:207], v203 offset:128
	ds_read_b128 v[208:211], v203 offset:160
	s_waitcnt lgkmcnt(0)
	v_mfma_f32_32x32x16_bf16 v[80:95], v[204:207], v[112:115], v[80:95]
	v_mfma_f32_32x32x16_bf16 v[64:79], v[204:207], v[132:135], v[64:79]
	v_mfma_f32_32x32x16_bf16 v[80:95], v[208:211], v[116:119], v[80:95]
	v_mfma_f32_32x32x16_bf16 v[64:79], v[208:211], v[140:143], v[64:79]
	s_setprio 0
	s_branch .LBB0_885

.LBB0_2117:
	v_mad_u32_u24 v203, v203, s81, v201
	ds_read_b128 v[204:207], v203
	ds_read_b128 v[208:211], v203 offset:32
	s_nop 5
	v_xor_b32_e32 v80, 0x80000000, v199
	v_xor_b32_e32 v64, 0x80000000, v200
	v_mov_b32_e32 v81, v80
	v_mov_b32_e32 v82, v80
	v_mov_b32_e32 v83, v80
	v_mov_b32_e32 v84, v80
	v_mov_b32_e32 v85, v80
	v_mov_b32_e32 v86, v80
	v_mov_b32_e32 v87, v80
	v_mov_b32_e32 v88, v80
	v_mov_b32_e32 v89, v80
	v_mov_b32_e32 v90, v80
	v_mov_b32_e32 v91, v80
	v_mov_b32_e32 v92, v80
	v_mov_b32_e32 v93, v80
	v_mov_b32_e32 v94, v80
	v_mov_b32_e32 v95, v80
	v_mov_b32_e32 v65, v64
	v_mov_b32_e32 v66, v64
	v_mov_b32_e32 v67, v64
	v_mov_b32_e32 v68, v64
	v_mov_b32_e32 v69, v64
	v_mov_b32_e32 v70, v64
	v_mov_b32_e32 v71, v64
	v_mov_b32_e32 v72, v64
	v_mov_b32_e32 v73, v64
	v_mov_b32_e32 v74, v64
	v_mov_b32_e32 v75, v64
	v_mov_b32_e32 v76, v64
	v_mov_b32_e32 v77, v64
	v_mov_b32_e32 v78, v64
	v_mov_b32_e32 v79, v64
	s_waitcnt lgkmcnt(0)
	s_setprio 1
	v_mfma_f32_32x32x16_bf16 v[80:95], v[204:207], v[96:99], v[80:95]
	v_mfma_f32_32x32x16_bf16 v[64:79], v[204:207], v[136:139], v[64:79]
	v_mfma_f32_32x32x16_bf16 v[80:95], v[208:211], v[100:103], v[80:95]
	v_mfma_f32_32x32x16_bf16 v[64:79], v[208:211], v[120:123], v[64:79]
	ds_read_b128 v[204:207], v203 offset:64
	ds_read_b128 v[208:211], v203 offset:96
	s_waitcnt lgkmcnt(0)
	v_mfma_f32_32x32x16_bf16 v[80:95], v[204:207], v[104:107], v[80:95]
	v_mfma_f32_32x32x16_bf16 v[64:79], v[204:207], v[124:127], v[64:79]
	v_mfma_f32_32x32x16_bf16 v[80:95], v[208:211], v[108:111], v[80:95]
	v_mfma_f32_32x32x16_bf16 v[64:79], v[208:211], v[128:131], v[64:79]
	ds_read_b128 v[204:207], v203 offset:128
	ds_read_b128 v[208:211], v203 offset:160
	s_waitcnt lgkmcnt(0)
	v_mfma_f32_32x32x16_bf16 v[80:95], v[204:207], v[112:115], v[80:95]
	v_mfma_f32_32x32x16_bf16 v[64:79], v[204:207], v[132:135], v[64:79]
	v_mfma_f32_32x32x16_bf16 v[80:95], v[208:211], v[116:119], v[80:95]
	v_mfma_f32_32x32x16_bf16 v[64:79], v[208:211], v[140:143], v[64:79]
	s_setprio 0
	s_branch .LBB0_2119
